# first attention item static (ticket contention at phase start removed); rnn2 items taken from a second ticket counter so they fill the attention tail
# speedup vs baseline: 1.1302x; 1.0234x over previous
; __device__ __forceinline__ int get_tid() { int t = threadIdx.x; asm volatile("" : "+v"(t)); return t; }
; __device__ __forceinline__ int get_bid() { int b = blockIdx.x; asm volatile("" : "+s"(b)); return b; }
; __device__ __forceinline__ bool gemm_ticket(unsigned* ctr, int nt, int& tm, int& tn, char* smem) {
;     int* sT = (int*)(smem + 32768 + 512);
;     const int xcd = get_bid() & 7;
;     if (get_tid() == 0) sT[0] = (int)atomicAdd(ctr + xcd * 32, 1u);
;     __syncthreads();
;     const int j = sT[0];
;     if (j >= 32 * nt) return false;
; __device__ void run_phase(const Params& p, int ph, char* smem) {
;     ...
;         for (int r = 0; r < nr; ++r) {
;             if (l == 0 && quant_first) do_quant(r);
;             const int pos = (r & 1) ? (G - 1 - get_bid()) : get_bid();
;             const int si = r * G + pos;
;             if (si < 2048) attn_item(p, si, smem);
.LBB0_101:
	s_cmp_eq_u32 s11, 0
	s_cbranch_scc0 .Ltk_dyn
	s_mov_b32 s15, s2
	v_mov_b32_e32 v0, 0x9c40
	v_mov_b32_e32 v1, s15
	ds_write_b32 v0, v1
	s_waitcnt lgkmcnt(0)
	s_cmpk_gt_i32 s15, 0x7ff
	s_cbranch_scc0 .LBB0_107
	s_branch .LBB0_104
.Ltk_dyn:
	s_waitcnt lgkmcnt(0)
	s_barrier
	v_cmp_eq_u32_e32 vcc, 0, v126
	s_and_saveexec_b64 s[98:99], vcc
	s_cbranch_execz .Ltk_skip
	v_readlane_b32 s12, v165, 2
	v_readlane_b32 s13, v165, 3
	v_readlane_b32 s15, v167, 36
	s_mul_i32 s15, s15, 0xc00
	s_addk_i32 s15, 0x840
	v_mov_b32_e32 v0, s15
	v_mov_b32_e32 v1, 1
	s_nop 2
	global_atomic_add v0, v0, v1, s[12:13] sc0
	v_mov_b32_e32 v1, 0x9c40
	s_waitcnt vmcnt(0)
	v_add_u32_e32 v0, s28, v0
	ds_write_b32 v1, v0

; __device__ __forceinline__ unsigned pk_bf16(float lo, float hi) { unsigned r; asm("v_cvt_pk_bf16_f32 %0, %1, %2" : "=v"(r) : "v"(lo), "v"(hi)); return r; }
; __device__ __forceinline__ float bflo(unsigned u) { return __uint_as_float(u << 16); }
; __device__ __forceinline__ float bfhi(unsigned u) { return __uint_as_float(u & 0xffff0000u); }
; __device__ __forceinline__ float gelu_tanh(float x) { const float u = 0.7978845608028654f * (x + 0.044715f * x * x * x); return x / (1.0f + __expf(-2.0f * u)); }
; __device__ void rnn2_item(const Params& p, int item, char* smem) {
;     ...
;     const int cc = tid & 7;
;     const f32x4 ca = *(const f32x4*)(sCarry + cc * 8), cb = *(const f32x4*)(sCarry + cc * 8 + 4);
;     const float cr[8] = {ca[0], ca[1], ca[2], ca[3], cb[0], cb[1], cb[2], cb[3]};
; #pragma unroll
;     for (int i = 0; i < 2; ++i) {
;         const size_t t = (size_t)b * S + t0 + (tid >> 3) + 32 * i;
;         const u32x4 h0 = *(const u32x4*)(p.HP + t * 256 + hb * 64 + cc * 8), h1 = *(const u32x4*)(p.HP + t * 256 + hb * 64 + cc * 8 + 4);
;         const u32x4 gt = *(const u32x4*)(p.proj + t * NIN + G0 + hb * 64 + cc * 8);
;         const unsigned hp[8] = {h0.x, h0.y, h0.z, h0.w, h1.x, h1.y, h1.z, h1.w};
;         const unsigned gw[4] = {gt.x, gt.y, gt.z, gt.w};
;         float o[8];
; #pragma unroll
;         for (int e = 0; e < 8; ++e) {
;             const float hfull = bflo(hp[e]) + bfhi(hp[e]) * cr[e];
;             const float gate = (e & 1) ? bfhi(gw[e >> 1]) : bflo(gw[e >> 1]);
;             o[e] = hfull * gelu_tanh(gate);
;         }
;         u32x4 w; w.x = pk_bf16(o[0], o[1]); w.y = pk_bf16(o[2], o[3]); w.z = pk_bf16(o[4], o[5]); w.w = pk_bf16(o[6], o[7]);
;         *(u32x4*)(p.mixed + t * 1024 + 768 + hb * 64 + cc * 8) = w;
.LBB0_140:
	s_waitcnt lgkmcnt(0)
	s_barrier
	v_cmp_eq_u32_e32 vcc, 0, v126
	s_and_saveexec_b64 s[98:99], vcc
	s_cbranch_execz .Ltk2_skip
	v_readlane_b32 s12, v165, 2
	v_readlane_b32 s13, v165, 3
	v_readlane_b32 s15, v167, 36
	s_mul_i32 s15, s15, 0xc00
	s_addk_i32 s15, 0x844
	v_mov_b32_e32 v0, s15
	v_mov_b32_e32 v1, 1
	s_nop 2
	global_atomic_add v0, v0, v1, s[12:13] sc0
	v_mov_b32_e32 v1, 0x9c40
	s_waitcnt vmcnt(0)
	ds_write_b32 v1, v0
.Ltk2_skip:
	s_or_b64 exec, exec, s[98:99]
	s_waitcnt lgkmcnt(0)
	s_barrier
	v_mov_b32_e32 v0, 0x9c40
	ds_read_b32 v0, v0
	s_waitcnt lgkmcnt(0)
	v_readfirstlane_b32 s10, v0
	s_cmpk_gt_i32 s10, 0x7ff
	s_cbranch_scc1 .LBB0_155
	s_lshl_b32 s11, s10, 6
	s_branch .LBB0_143
.LBB0_142:
	s_or_b64 exec, exec, s[22:23]
	s_lshl_b32 s12, s12, 6
	s_lshl_b64 s[0:1], s[0:1], 13
	v_ashrrev_i32_e32 v8, 3, v36
	v_ashrrev_i32_e32 v9, 31, v8
	s_or_b32 s0, s0, s12
	s_lshl_b32 s13, s10, 6
	v_lshl_add_u64 v[22:23], s[0:1], 0, v[8:9]
	v_readlane_b32 s36, v165, 26
	s_and_b32 s13, s13, 0xc0
	v_lshlrev_b32_e32 v0, 3, v36
	v_lshlrev_b64 v[8:9], 10, v[22:23]
	v_readlane_b32 s37, v165, 27
	v_and_b32_e32 v10, 56, v0
	s_lshl_b32 s20, s13, 2
	v_lshl_add_u64 v[8:9], s[36:37], 0, v[8:9]
	v_lshlrev_b32_e32 v112, 2, v10
	v_lshl_add_u64 v[8:9], v[8:9], 0, s[20:21]
	v_lshl_add_u64 v[8:9], v[8:9], 0, v[112:113]
	s_waitcnt lgkmcnt(0)
	s_barrier
	ds_read_b128 v[0:3], v112
	ds_read_b128 v[4:7], v112 offset:16
	global_load_dwordx4 v[12:15], v[8:9], off offset:16
	global_load_dwordx4 v[16:19], v[8:9], off
	v_mov_b64_e32 v[8:9], s[90:91]
	v_mad_u64_u32 v[8:9], s[0:1], v22, s29, v[8:9]
	v_mad_i32_i24 v9, v23, s29, v9
	s_lshl_b32 s0, s13, 1
	s_mov_b32 s1, s21
	v_lshlrev_b32_e32 v20, 1, v10
	v_mov_b32_e32 v21, v113
	v_lshl_add_u64 v[8:9], v[8:9], 0, s[0:1]
	v_lshl_add_u64 v[24:25], v[8:9], 0, v[20:21]
	s_movk_i32 s12, 0x1000
	v_add_co_u32_e32 v8, vcc, s12, v24
	v_readlane_b32 s14, v165, 8
	s_nop 0
	v_addc_co_u32_e32 v9, vcc, 0, v25, vcc
	global_load_dwordx4 v[8:11], v[8:9], off offset:528
	v_readlane_b32 s15, v165, 9
	s_add_i32 s10, s10, s28
	v_readlane_b32 s38, v165, 28
	v_readlane_b32 s39, v165, 29
	v_readlane_b32 s40, v165, 30
	v_readlane_b32 s41, v165, 31
	v_readlane_b32 s42, v165, 32
	v_readlane_b32 s43, v165, 33
	v_readlane_b32 s44, v165, 34
	v_readlane_b32 s45, v165, 35
	v_readlane_b32 s46, v165, 36
	v_readlane_b32 s47, v165, 37
	v_readlane_b32 s48, v165, 38
	v_readlane_b32 s49, v165, 39
	v_readlane_b32 s50, v165, 40
	v_readlane_b32 s51, v165, 41
	s_waitcnt vmcnt(1)
	v_lshlrev_b32_e32 v114, 16, v16
	v_and_b32_e32 v16, 0xffff0000, v16
	s_waitcnt lgkmcnt(1)
	v_mul_f32_e32 v26, v0, v16
	s_waitcnt vmcnt(0)
	v_lshlrev_b32_e32 v16, 16, v8
	v_mul_f32_e32 v27, 0x3d372713, v16
	v_mul_f32_e32 v27, v27, v16
	v_fma_f32 v27, v27, v16, v16
	v_mul_f32_e32 v27, 0x3f4c422a, v27
	v_mul_f32_e32 v27, -2.0, v27
	v_mul_f32_e32 v27, 0x3fb8aa3b, v27
	v_exp_f32_e32 v27, v27
	v_and_b32_e32 v8, 0xffff0000, v8
	v_pk_add_f32 v[26:27], v[26:27], v[114:115]
	s_nop 0
	v_div_scale_f32 v28, s[12:13], v27, v27, v16
	v_rcp_f32_e32 v29, v28
	v_lshlrev_b32_e32 v114, 16, v17
	v_and_b32_e32 v17, 0xffff0000, v17
	v_fma_f32 v30, -v28, v29, 1.0
	v_fmac_f32_e32 v29, v30, v29
	v_div_scale_f32 v30, vcc, v16, v27, v16
	v_mul_f32_e32 v31, v30, v29
	v_fma_f32 v32, -v28, v31, v30
	v_fmac_f32_e32 v31, v32, v29
	v_fma_f32 v28, -v28, v31, v30
	v_div_fmas_f32 v28, v28, v29, v31
	v_div_fixup_f32 v16, v28, v27, v16
	v_mul_f32_e32 v16, v26, v16
	v_mul_f32_e32 v26, v1, v17
	v_mul_f32_e32 v17, 0x3d372713, v8
	v_mul_f32_e32 v17, v17, v8
	v_fma_f32 v17, v17, v8, v8
	v_mul_f32_e32 v17, 0x3f4c422a, v17
	v_mul_f32_e32 v17, -2.0, v17
	v_mul_f32_e32 v17, 0x3fb8aa3b, v17
	v_exp_f32_e32 v27, v17
	s_nop 0
	v_pk_add_f32 v[26:27], v[26:27], v[114:115]
	s_nop 0
	v_div_scale_f32 v17, s[12:13], v27, v27, v8
	v_rcp_f32_e32 v28, v17
	v_lshlrev_b32_e32 v114, 16, v18
	v_fma_f32 v29, -v17, v28, 1.0
	v_fmac_f32_e32 v28, v29, v28
	v_div_scale_f32 v29, vcc, v8, v27, v8
	v_mul_f32_e32 v30, v29, v28
	v_fma_f32 v31, -v17, v30, v29
	v_fmac_f32_e32 v30, v31, v28
	v_fma_f32 v17, -v17, v30, v29
	v_div_fmas_f32 v17, v17, v28, v30
	v_div_fixup_f32 v8, v17, v27, v8
	v_mul_f32_e32 v17, v26, v8
	v_and_b32_e32 v8, 0xffff0000, v18
	v_mul_f32_e32 v26, v2, v8
	v_lshlrev_b32_e32 v8, 16, v9
	v_mul_f32_e32 v18, 0x3d372713, v8
	v_mul_f32_e32 v18, v18, v8
	v_fma_f32 v18, v18, v8, v8
	v_mul_f32_e32 v18, 0x3f4c422a, v18
	v_mul_f32_e32 v18, -2.0, v18
	v_mul_f32_e32 v18, 0x3fb8aa3b, v18
	v_exp_f32_e32 v27, v18
	s_nop 0
	v_pk_add_f32 v[26:27], v[26:27], v[114:115]
	s_nop 0
	v_div_scale_f32 v18, s[12:13], v27, v27, v8
	v_rcp_f32_e32 v28, v18
	v_lshlrev_b32_e32 v114, 16, v19
	v_fma_f32 v29, -v18, v28, 1.0
	v_fmac_f32_e32 v28, v29, v28
	v_div_scale_f32 v29, vcc, v8, v27, v8
	v_mul_f32_e32 v30, v29, v28
	v_fma_f32 v31, -v18, v30, v29
	v_fmac_f32_e32 v30, v31, v28
	v_fma_f32 v18, -v18, v30, v29
	v_div_fmas_f32 v18, v18, v28, v30
	v_div_fixup_f32 v8, v18, v27, v8
	v_mul_f32_e32 v18, v26, v8
	v_and_b32_e32 v8, 0xffff0000, v19
	v_and_b32_e32 v19, 0xffff0000, v9
	v_mul_f32_e32 v9, 0x3d372713, v19
	v_mul_f32_e32 v9, v9, v19
	v_fma_f32 v9, v9, v19, v19
	v_mul_f32_e32 v9, 0x3f4c422a, v9
	v_mul_f32_e32 v9, -2.0, v9
	v_mul_f32_e32 v9, 0x3fb8aa3b, v9
	v_exp_f32_e32 v9, v9
	v_mul_f32_e32 v8, v3, v8
	v_pk_add_f32 v[8:9], v[8:9], v[114:115]
	s_nop 0
	v_div_scale_f32 v26, s[12:13], v9, v9, v19
	v_rcp_f32_e32 v27, v26
	v_lshlrev_b32_e32 v114, 16, v12
	v_fma_f32 v28, -v26, v27, 1.0
	v_fmac_f32_e32 v27, v28, v27
	v_div_scale_f32 v28, vcc, v19, v9, v19
	v_mul_f32_e32 v29, v28, v27
	v_fma_f32 v30, -v26, v29, v28
	v_fmac_f32_e32 v29, v30, v27
	v_fma_f32 v26, -v26, v29, v28
	v_div_fmas_f32 v26, v26, v27, v29
	v_div_fixup_f32 v9, v26, v9, v19
	v_mul_f32_e32 v8, v8, v9
	v_and_b32_e32 v9, 0xffff0000, v12
	s_waitcnt lgkmcnt(0)
; __device__ __forceinline__ unsigned pk_bf16(float lo, float hi) { unsigned r; asm("v_cvt_pk_bf16_f32 %0, %1, %2" : "=v"(r) : "v"(lo), "v"(hi)); return r; }
; __device__ __forceinline__ float bflo(unsigned u) { return __uint_as_float(u << 16); }
; __device__ __forceinline__ float bfhi(unsigned u) { return __uint_as_float(u & 0xffff0000u); }
; __device__ __forceinline__ float gelu_tanh(float x) { const float u = 0.7978845608028654f * (x + 0.044715f * x * x * x); return x / (1.0f + __expf(-2.0f * u)); }
; __device__ void rnn2_item(const Params& p, int item, char* smem) {
;     ...
;         float o[8];
; #pragma unroll
;         for (int e = 0; e < 8; ++e) {
;             const float hfull = bflo(hp[e]) + bfhi(hp[e]) * cr[e];
;             const float gate = (e & 1) ? bfhi(gw[e >> 1]) : bflo(gw[e >> 1]);
;             o[e] = hfull * gelu_tanh(gate);
;         }
;         u32x4 w; w.x = pk_bf16(o[0], o[1]); w.y = pk_bf16(o[2], o[3]); w.z = pk_bf16(o[4], o[5]); w.w = pk_bf16(o[6], o[7]);
;         *(u32x4*)(p.mixed + t * 1024 + 768 + hb * 64 + cc * 8) = w;
	v_mul_f32_e32 v26, v4, v9
	v_lshlrev_b32_e32 v9, 16, v10
	v_mul_f32_e32 v12, 0x3d372713, v9
	v_mul_f32_e32 v12, v12, v9
	v_fma_f32 v12, v12, v9, v9
	v_mul_f32_e32 v12, 0x3f4c422a, v12
	v_mul_f32_e32 v12, -2.0, v12
	v_mul_f32_e32 v12, 0x3fb8aa3b, v12
	v_exp_f32_e32 v27, v12
	v_and_b32_e32 v10, 0xffff0000, v10
	v_pk_add_f32 v[26:27], v[26:27], v[114:115]
	s_nop 0
	v_div_scale_f32 v12, s[12:13], v27, v27, v9
	v_rcp_f32_e32 v19, v12
	v_lshlrev_b32_e32 v114, 16, v13
	v_fma_f32 v28, -v12, v19, 1.0
	v_fmac_f32_e32 v19, v28, v19
	v_div_scale_f32 v28, vcc, v9, v27, v9
	v_mul_f32_e32 v29, v28, v19
	v_fma_f32 v30, -v12, v29, v28
	v_fmac_f32_e32 v29, v30, v19
	v_fma_f32 v12, -v12, v29, v28
	v_div_fmas_f32 v12, v12, v19, v29
	v_div_fixup_f32 v9, v12, v27, v9
	v_and_b32_e32 v12, 0xffff0000, v13
	v_mul_f32_e32 v13, 0x3d372713, v10
	v_mul_f32_e32 v13, v13, v10
	v_fma_f32 v13, v13, v10, v10
	v_mul_f32_e32 v13, 0x3f4c422a, v13
	v_mul_f32_e32 v13, -2.0, v13
	v_mul_f32_e32 v13, 0x3fb8aa3b, v13
	v_exp_f32_e32 v13, v13
	v_mul_f32_e32 v12, v5, v12
	v_mul_f32_e32 v9, v26, v9
	v_pk_add_f32 v[12:13], v[12:13], v[114:115]
	s_nop 0
	v_div_scale_f32 v19, s[12:13], v13, v13, v10
	v_rcp_f32_e32 v26, v19
	v_lshlrev_b32_e32 v114, 16, v14
	v_fma_f32 v27, -v19, v26, 1.0
	v_fmac_f32_e32 v26, v27, v26
	v_div_scale_f32 v27, vcc, v10, v13, v10
	v_mul_f32_e32 v28, v27, v26
	v_fma_f32 v29, -v19, v28, v27
	v_fmac_f32_e32 v28, v29, v26
	v_fma_f32 v19, -v19, v28, v27
	v_div_fmas_f32 v19, v19, v26, v28
	v_div_fixup_f32 v10, v19, v13, v10
	v_mul_f32_e32 v19, v12, v10
	v_and_b32_e32 v10, 0xffff0000, v14
	v_mul_f32_e32 v12, v6, v10
	v_lshlrev_b32_e32 v10, 16, v11
	v_mul_f32_e32 v13, 0x3d372713, v10
	v_mul_f32_e32 v13, v13, v10
	v_fma_f32 v13, v13, v10, v10
	v_mul_f32_e32 v13, 0x3f4c422a, v13
	v_mul_f32_e32 v13, -2.0, v13
	v_mul_f32_e32 v13, 0x3fb8aa3b, v13
	v_exp_f32_e32 v13, v13
	s_nop 0
	v_pk_add_f32 v[12:13], v[12:13], v[114:115]
	s_nop 0
	v_div_scale_f32 v14, s[12:13], v13, v13, v10
	v_rcp_f32_e32 v26, v14
	v_lshlrev_b32_e32 v114, 16, v15
	v_fma_f32 v27, -v14, v26, 1.0
	v_fmac_f32_e32 v26, v27, v26
	v_div_scale_f32 v27, vcc, v10, v13, v10
	v_mul_f32_e32 v28, v27, v26
	v_fma_f32 v29, -v14, v28, v27
	v_fmac_f32_e32 v28, v29, v26
	v_fma_f32 v14, -v14, v28, v27
	v_div_fmas_f32 v14, v14, v26, v28
	v_div_fixup_f32 v10, v14, v13, v10
	v_mul_f32_e32 v13, v12, v10
	v_and_b32_e32 v12, 0xffff0000, v11
	v_mul_f32_e32 v11, 0x3d372713, v12
	v_mul_f32_e32 v11, v11, v12
	v_fma_f32 v11, v11, v12, v12
	v_mul_f32_e32 v11, 0x3f4c422a, v11
	v_mul_f32_e32 v11, -2.0, v11
	v_mul_f32_e32 v11, 0x3fb8aa3b, v11
	v_exp_f32_e32 v11, v11
	v_and_b32_e32 v10, 0xffff0000, v15
	v_mul_f32_e32 v10, v7, v10
	v_pk_add_f32 v[10:11], v[10:11], v[114:115]
	s_nop 0
	v_div_scale_f32 v14, s[12:13], v11, v11, v12
	v_rcp_f32_e32 v15, v14
	s_mov_b32 s12, 0x29000
	v_fma_f32 v26, -v14, v15, 1.0
	v_fmac_f32_e32 v15, v26, v15
	v_div_scale_f32 v26, vcc, v12, v11, v12
	v_mul_f32_e32 v27, v26, v15
	v_fma_f32 v28, -v14, v27, v26
	v_fmac_f32_e32 v27, v28, v15
	v_fma_f32 v14, -v14, v27, v26
	v_div_fmas_f32 v14, v14, v15, v27
	v_div_fixup_f32 v11, v14, v11, v12
	v_mul_f32_e32 v14, v10, v11
	v_cvt_pk_bf16_f32 v11, v18, v8
	v_cvt_pk_bf16_f32 v12, v9, v19
	v_lshlrev_b64 v[8:9], 11, v[22:23]
	v_lshl_add_u64 v[8:9], s[14:15], 0, v[8:9]
	v_lshl_add_u64 v[8:9], v[8:9], 0, s[0:1]
	v_lshl_add_u64 v[8:9], v[8:9], 0, v[20:21]
	v_lshl_add_u64 v[22:23], v[22:23], 0, 32
	v_cvt_pk_bf16_f32 v10, v16, v17
	v_cvt_pk_bf16_f32 v13, v13, v14
	global_store_dwordx4 v[8:9], v[10:13], off offset:1536
	v_lshlrev_b64 v[8:9], 10, v[22:23]
	v_lshl_add_u64 v[8:9], s[36:37], 0, v[8:9]
	v_lshl_add_u64 v[8:9], v[8:9], 0, s[20:21]
	v_lshl_add_u64 v[12:13], v[8:9], 0, v[112:113]
	global_load_dwordx4 v[8:11], v[12:13], off
	global_load_dwordx4 v[16:19], v[12:13], off offset:16
	v_add_co_u32_e32 v12, vcc, s12, v24
	s_waitcnt vmcnt(0)
	v_and_b32_e32 v24, 0xffff0000, v19
	v_addc_co_u32_e32 v13, vcc, 0, v25, vcc
	global_load_dwordx4 v[12:15], v[12:13], off offset:1040
	v_mul_f32_e32 v24, v7, v24
	v_and_b32_e32 v7, 0xffff0000, v18
	v_mul_f32_e32 v6, v6, v7
	v_lshlrev_b32_e32 v114, 16, v18
	v_lshlrev_b32_e32 v26, 16, v19
	s_waitcnt vmcnt(0)
; __device__ __forceinline__ unsigned pk_bf16(float lo, float hi) { unsigned r; asm("v_cvt_pk_bf16_f32 %0, %1, %2" : "=v"(r) : "v"(lo), "v"(hi)); return r; }
; __device__ __forceinline__ float bflo(unsigned u) { return __uint_as_float(u << 16); }
; __device__ __forceinline__ float bfhi(unsigned u) { return __uint_as_float(u & 0xffff0000u); }
; __device__ __forceinline__ float gelu_tanh(float x) { const float u = 0.7978845608028654f * (x + 0.044715f * x * x * x); return x / (1.0f + __expf(-2.0f * u)); }
; __device__ void rnn2_item(const Params& p, int item, char* smem) {
;     ...
;         float o[8];
; #pragma unroll
;         for (int e = 0; e < 8; ++e) {
;             const float hfull = bflo(hp[e]) + bfhi(hp[e]) * cr[e];
;             const float gate = (e & 1) ? bfhi(gw[e >> 1]) : bflo(gw[e >> 1]);
;             o[e] = hfull * gelu_tanh(gate);
;         }
;         u32x4 w; w.x = pk_bf16(o[0], o[1]); w.y = pk_bf16(o[2], o[3]); w.z = pk_bf16(o[4], o[5]); w.w = pk_bf16(o[6], o[7]);
;         *(u32x4*)(p.mixed + t * 1024 + 768 + hb * 64 + cc * 8) = w;
;     }
;     __syncthreads();
	v_and_b32_e32 v28, 0xffff0000, v15
	v_lshlrev_b32_e32 v15, 16, v15
	v_mul_f32_e32 v7, 0x3d372713, v15
	v_mul_f32_e32 v7, v7, v15
	v_fma_f32 v7, v7, v15, v15
	v_mul_f32_e32 v7, 0x3f4c422a, v7
	v_mul_f32_e32 v7, -2.0, v7
	v_mul_f32_e32 v7, 0x3fb8aa3b, v7
	v_exp_f32_e32 v7, v7
	s_nop 0
	v_pk_add_f32 v[6:7], v[6:7], v[114:115]
	s_nop 0
	v_div_scale_f32 v18, s[12:13], v7, v7, v15
	v_rcp_f32_e32 v19, v18
	v_lshlrev_b32_e32 v114, 16, v17
	v_fma_f32 v25, -v18, v19, 1.0
	v_fmac_f32_e32 v19, v25, v19
	v_div_scale_f32 v25, vcc, v15, v7, v15
	v_mul_f32_e32 v27, v25, v19
	v_fma_f32 v29, -v18, v27, v25
	v_fmac_f32_e32 v27, v29, v19
	v_fma_f32 v18, -v18, v27, v25
	v_div_fmas_f32 v18, v18, v19, v27
	v_div_fixup_f32 v7, v18, v7, v15
	v_mul_f32_e32 v6, v6, v7
	v_and_b32_e32 v7, 0xffff0000, v17
	v_mul_f32_e32 v18, v5, v7
	v_and_b32_e32 v5, 0xffff0000, v14
	v_mul_f32_e32 v7, 0x3d372713, v5
	v_mul_f32_e32 v7, v7, v5
	v_fma_f32 v7, v7, v5, v5
	v_mul_f32_e32 v7, 0x3f4c422a, v7
	v_mul_f32_e32 v7, -2.0, v7
	v_mul_f32_e32 v7, 0x3fb8aa3b, v7
	v_exp_f32_e32 v19, v7
	s_nop 0
	v_pk_add_f32 v[18:19], v[18:19], v[114:115]
	s_nop 0
	v_div_scale_f32 v7, s[12:13], v19, v19, v5
	v_rcp_f32_e32 v15, v7
	v_lshlrev_b32_e32 v114, 16, v16
	v_fma_f32 v17, -v7, v15, 1.0
	v_fmac_f32_e32 v15, v17, v15
	v_div_scale_f32 v17, vcc, v5, v19, v5
	v_mul_f32_e32 v25, v17, v15
	v_fma_f32 v27, -v7, v25, v17
	v_fmac_f32_e32 v25, v27, v15
	v_fma_f32 v7, -v7, v25, v17
	v_div_fmas_f32 v7, v7, v15, v25
	v_div_fixup_f32 v5, v7, v19, v5
	v_and_b32_e32 v7, 0xffff0000, v16
	v_mul_f32_e32 v5, v18, v5
	v_mul_f32_e32 v18, v4, v7
	v_lshlrev_b32_e32 v4, 16, v14
	v_mul_f32_e32 v7, 0x3d372713, v4
	v_mul_f32_e32 v7, v7, v4
	v_fma_f32 v7, v7, v4, v4
	v_mul_f32_e32 v7, 0x3f4c422a, v7
	v_mul_f32_e32 v7, -2.0, v7
	v_mul_f32_e32 v7, 0x3fb8aa3b, v7
	v_exp_f32_e32 v19, v7
	v_mov_b32_e32 v27, v115
	v_pk_add_f32 v[14:15], v[18:19], v[114:115]
	s_nop 0
	v_div_scale_f32 v7, s[12:13], v15, v15, v4
	v_rcp_f32_e32 v16, v7
	v_lshlrev_b32_e32 v114, 16, v11
	v_fma_f32 v17, -v7, v16, 1.0
	v_fmac_f32_e32 v16, v17, v16
	v_div_scale_f32 v17, vcc, v4, v15, v4
	v_mul_f32_e32 v18, v17, v16
	v_fma_f32 v19, -v7, v18, v17
	v_fmac_f32_e32 v18, v19, v16
	v_fma_f32 v7, -v7, v18, v17
	v_div_fmas_f32 v7, v7, v16, v18
	v_div_fixup_f32 v4, v7, v15, v4
	v_and_b32_e32 v7, 0xffff0000, v11
	v_mul_f32_e32 v4, v14, v4
	v_mul_f32_e32 v14, v3, v7
	v_and_b32_e32 v3, 0xffff0000, v13
	v_mul_f32_e32 v7, 0x3d372713, v3
	v_mul_f32_e32 v7, v7, v3
	v_fma_f32 v7, v7, v3, v3
	v_mul_f32_e32 v7, 0x3f4c422a, v7
	v_mul_f32_e32 v7, -2.0, v7
	v_mul_f32_e32 v7, 0x3fb8aa3b, v7
	v_exp_f32_e32 v15, v7
	s_nop 0
	v_pk_add_f32 v[14:15], v[14:15], v[114:115]
	s_nop 0
	v_div_scale_f32 v7, s[12:13], v15, v15, v3
	v_rcp_f32_e32 v11, v7
	v_lshlrev_b32_e32 v114, 16, v10
	v_fma_f32 v16, -v7, v11, 1.0
	v_fmac_f32_e32 v11, v16, v11
	v_div_scale_f32 v16, vcc, v3, v15, v3
	v_mul_f32_e32 v17, v16, v11
	v_fma_f32 v18, -v7, v17, v16
	v_fmac_f32_e32 v17, v18, v11
	v_fma_f32 v7, -v7, v17, v16
	v_div_fmas_f32 v7, v7, v11, v17
	v_div_fixup_f32 v3, v7, v15, v3
	v_and_b32_e32 v7, 0xffff0000, v10
	v_mul_f32_e32 v3, v14, v3
	v_mul_f32_e32 v14, v2, v7
	v_lshlrev_b32_e32 v2, 16, v13
	v_mul_f32_e32 v7, 0x3d372713, v2
	v_mul_f32_e32 v7, v7, v2
	v_fma_f32 v7, v7, v2, v2
	v_mul_f32_e32 v7, 0x3f4c422a, v7
	v_mul_f32_e32 v7, -2.0, v7
	v_mul_f32_e32 v7, 0x3fb8aa3b, v7
	v_exp_f32_e32 v15, v7
	s_nop 0
	v_pk_add_f32 v[10:11], v[14:15], v[114:115]
	s_nop 0
	v_div_scale_f32 v7, s[12:13], v11, v11, v2
	v_rcp_f32_e32 v13, v7
	v_lshlrev_b32_e32 v114, 16, v9
	v_fma_f32 v14, -v7, v13, 1.0
	v_fmac_f32_e32 v13, v14, v13
	v_div_scale_f32 v14, vcc, v2, v11, v2
	v_mul_f32_e32 v15, v14, v13
	v_fma_f32 v16, -v7, v15, v14
	v_fmac_f32_e32 v15, v16, v13
	v_fma_f32 v7, -v7, v15, v14
	v_div_fmas_f32 v7, v7, v13, v15
	v_div_fixup_f32 v2, v7, v11, v2
	v_and_b32_e32 v7, 0xffff0000, v9
	v_mul_f32_e32 v2, v10, v2
	v_mul_f32_e32 v10, v1, v7
	v_and_b32_e32 v1, 0xffff0000, v12
	v_mul_f32_e32 v7, 0x3d372713, v1
	v_mul_f32_e32 v7, v7, v1
	v_fma_f32 v7, v7, v1, v1
	v_mul_f32_e32 v7, 0x3f4c422a, v7
	v_mul_f32_e32 v7, -2.0, v7
	v_mul_f32_e32 v7, 0x3fb8aa3b, v7
	v_exp_f32_e32 v11, v7
	s_nop 0
	v_pk_add_f32 v[10:11], v[10:11], v[114:115]
	s_nop 0
	v_div_scale_f32 v7, s[12:13], v11, v11, v1
	v_rcp_f32_e32 v9, v7
	v_lshlrev_b32_e32 v114, 16, v8
	v_fma_f32 v13, -v7, v9, 1.0
	v_fmac_f32_e32 v9, v13, v9
	v_div_scale_f32 v13, vcc, v1, v11, v1
	v_mul_f32_e32 v14, v13, v9
	v_fma_f32 v15, -v7, v14, v13
	v_fmac_f32_e32 v14, v15, v9
	v_fma_f32 v7, -v7, v14, v13
	v_div_fmas_f32 v7, v7, v9, v14
	v_div_fixup_f32 v1, v7, v11, v1
	v_mul_f32_e32 v7, v10, v1
	v_and_b32_e32 v1, 0xffff0000, v8
	v_lshlrev_b32_e32 v8, 16, v12
	v_mul_f32_e32 v0, v0, v1
	v_mul_f32_e32 v1, 0x3d372713, v8
	v_mul_f32_e32 v1, v1, v8
	v_fma_f32 v1, v1, v8, v8
	v_mul_f32_e32 v1, 0x3f4c422a, v1
	v_mul_f32_e32 v1, -2.0, v1
	v_mul_f32_e32 v1, 0x3fb8aa3b, v1
	v_exp_f32_e32 v1, v1
	s_nop 0
	v_pk_add_f32 v[0:1], v[0:1], v[114:115]
	s_nop 0
	v_div_scale_f32 v9, s[12:13], v1, v1, v8
	v_rcp_f32_e32 v10, v9
	s_nop 0
	v_fma_f32 v11, -v9, v10, 1.0
	v_fmac_f32_e32 v10, v11, v10
	v_div_scale_f32 v11, vcc, v8, v1, v8
	v_mul_f32_e32 v12, v11, v10
	v_fma_f32 v13, -v9, v12, v11
	v_fmac_f32_e32 v12, v13, v10
	v_fma_f32 v9, -v9, v12, v11
	v_div_fmas_f32 v9, v9, v10, v12
	v_div_fixup_f32 v1, v9, v1, v8
	v_mul_f32_e32 v8, v0, v1
	v_mul_f32_e32 v0, 0x3d372713, v28
	v_mul_f32_e32 v0, v0, v28
	v_fma_f32 v0, v0, v28, v28
	v_mul_f32_e32 v0, 0x3f4c422a, v0
	v_mul_f32_e32 v0, -2.0, v0
	v_mul_f32_e32 v0, 0x3fb8aa3b, v0
	v_exp_f32_e32 v25, v0
	s_nop 0
	v_pk_add_f32 v[0:1], v[24:25], v[26:27]
	s_nop 0
	v_div_scale_f32 v9, s[12:13], v1, v1, v28
	v_rcp_f32_e32 v10, v9
	s_nop 0
	v_fma_f32 v11, -v9, v10, 1.0
	v_fmac_f32_e32 v10, v11, v10
	v_div_scale_f32 v11, vcc, v28, v1, v28
	v_mul_f32_e32 v12, v11, v10
	v_fma_f32 v13, -v9, v12, v11
	v_fmac_f32_e32 v12, v13, v10
	v_fma_f32 v9, -v9, v12, v11
	v_div_fmas_f32 v9, v9, v10, v12
	v_div_fixup_f32 v1, v9, v1, v28
	v_mul_f32_e32 v9, v0, v1
	v_cvt_pk_bf16_f32 v1, v2, v3
	v_cvt_pk_bf16_f32 v2, v4, v5
	v_lshlrev_b64 v[4:5], 11, v[22:23]
	v_lshl_add_u64 v[4:5], s[14:15], 0, v[4:5]
	v_lshl_add_u64 v[4:5], v[4:5], 0, s[0:1]
	v_readlane_b32 s0, v167, 10
	s_add_i32 s11, s11, s0
	v_lshl_add_u64 v[4:5], v[4:5], 0, v[20:21]
	s_cmpk_gt_i32 s10, 0x7ff
	v_cvt_pk_bf16_f32 v0, v8, v7
	v_cvt_pk_bf16_f32 v3, v6, v9
	global_store_dwordx4 v[4:5], v[0:3], off offset:1536
	s_barrier
	s_branch .LBB0_140
